# P0U: phase-0 modulation GEMV k-loop unrolled by two with a second register set: 8 instead of 4 weight loads per wave in flight (on top of C6+N3)
# baseline (speedup 1.0000x reference)
.LBB0_442:
	v_lshl_add_u64 v[36:37], v[26:27], 0, s[6:7]
	v_add_co_u32_e64 v38, s[38:39], s97, v36
	global_load_dwordx4 v[32:35], v[36:37], off
	s_nop 0
	v_addc_co_u32_e64 v39, s[38:39], 0, v37, s[38:39]
	v_add_co_u32_e64 v40, s[38:39], s93, v36
	s_mov_b32 s1, 0x12000
	s_nop 0
	v_addc_co_u32_e64 v41, s[38:39], 0, v37, s[38:39]
	v_add_co_u32_e64 v44, s[38:39], s1, v36
	s_add_u32 s6, s6, 0x18000
	s_addc_u32 s7, s7, 0
	s_nop 0
	v_addc_co_u32_e64 v45, s[38:39], 0, v37, s[38:39]
	global_load_dwordx4 v[36:39], v[38:39], off
	s_nop 0
	global_load_dwordx4 v[40:43], v[40:41], off
	s_nop 0
	global_load_dwordx4 v[44:47], v[44:45], off
	v_lshl_add_u64 v[84:85], v[26:27], 0, s[6:7]
	v_add_co_u32_e64 v86, s[38:39], s97, v84
	global_load_dwordx4 v[80:83], v[84:85], off
	s_nop 0
	v_addc_co_u32_e64 v87, s[38:39], 0, v85, s[38:39]
	v_add_co_u32_e64 v88, s[38:39], s93, v84
	s_mov_b32 s1, 0x12000
	s_nop 0
	v_addc_co_u32_e64 v89, s[38:39], 0, v85, s[38:39]
	v_add_co_u32_e64 v92, s[38:39], s1, v84
	s_add_u32 s6, s6, 0x18000
	s_addc_u32 s7, s7, 0
	s_nop 0
	v_addc_co_u32_e64 v93, s[38:39], 0, v85, s[38:39]
	global_load_dwordx4 v[84:87], v[86:87], off
	s_nop 0
	global_load_dwordx4 v[88:91], v[88:89], off
	s_nop 0
	global_load_dwordx4 v[92:95], v[92:93], off
	ds_read_b128 v[48:51], v25 offset:8192
	ds_read_b128 v[52:55], v25 offset:16384
	ds_read_b128 v[56:59], v25 offset:24576
	ds_read_b128 v[60:63], v25
	ds_read_b128 v[64:67], v25 offset:32768
	s_waitcnt lgkmcnt(4)
	v_mov_b32_e32 v70, v51
	s_waitcnt lgkmcnt(3)
	v_mov_b32_e32 v72, v55
	s_waitcnt lgkmcnt(1)
	v_mov_b32_e32 v68, v63
	v_add_u32_e32 v25, 16, v25
	s_waitcnt vmcnt(7)
	v_pk_fma_f32 v[4:5], v[60:61], v[32:33], v[4:5] op_sel_hi:[0,1,1]
	v_pk_fma_f32 v[6:7], v[60:61], v[34:35], v[6:7] op_sel_hi:[0,1,1]
	v_pk_fma_f32 v[16:17], v[32:33], v[48:49], v[16:17] op_sel_hi:[1,0,1]
	v_pk_fma_f32 v[18:19], v[34:35], v[48:49], v[18:19] op_sel_hi:[1,0,1]
	v_pk_fma_f32 v[12:13], v[32:33], v[52:53], v[12:13] op_sel_hi:[1,0,1]
	v_pk_fma_f32 v[14:15], v[34:35], v[52:53], v[14:15] op_sel_hi:[1,0,1]
	v_pk_fma_f32 v[8:9], v[32:33], v[56:57], v[8:9] op_sel_hi:[1,0,1]
	v_pk_fma_f32 v[10:11], v[34:35], v[56:57], v[10:11] op_sel_hi:[1,0,1]
	s_waitcnt lgkmcnt(0)
	v_pk_fma_f32 v[0:1], v[32:33], v[64:65], v[0:1] op_sel_hi:[1,0,1]
	v_pk_fma_f32 v[2:3], v[34:35], v[64:65], v[2:3] op_sel_hi:[1,0,1]
	v_mov_b32_e32 v32, v59
	s_waitcnt vmcnt(6)
	v_pk_fma_f32 v[4:5], v[60:61], v[36:37], v[4:5] op_sel:[1,0,0]
	v_pk_fma_f32 v[6:7], v[60:61], v[38:39], v[6:7] op_sel:[1,0,0]
	v_pk_fma_f32 v[16:17], v[36:37], v[48:49], v[16:17] op_sel:[0,1,0]
	v_pk_fma_f32 v[18:19], v[38:39], v[48:49], v[18:19] op_sel:[0,1,0]
	v_pk_fma_f32 v[12:13], v[36:37], v[52:53], v[12:13] op_sel:[0,1,0]
	v_pk_fma_f32 v[14:15], v[38:39], v[52:53], v[14:15] op_sel:[0,1,0]
	v_pk_fma_f32 v[8:9], v[36:37], v[56:57], v[8:9] op_sel:[0,1,0]
	v_pk_fma_f32 v[10:11], v[38:39], v[56:57], v[10:11] op_sel:[0,1,0]
	v_pk_fma_f32 v[0:1], v[36:37], v[64:65], v[0:1] op_sel:[0,1,0]
	v_pk_fma_f32 v[2:3], v[38:39], v[64:65], v[2:3] op_sel:[0,1,0]
	v_mov_b32_e32 v34, v67
	s_waitcnt vmcnt(5)
	v_pk_fma_f32 v[4:5], v[62:63], v[40:41], v[4:5] op_sel_hi:[0,1,1]
	v_pk_fma_f32 v[6:7], v[62:63], v[42:43], v[6:7] op_sel_hi:[0,1,1]
	v_pk_fma_f32 v[16:17], v[40:41], v[50:51], v[16:17] op_sel_hi:[1,0,1]
	v_pk_fma_f32 v[18:19], v[42:43], v[50:51], v[18:19] op_sel_hi:[1,0,1]
	v_pk_fma_f32 v[12:13], v[40:41], v[54:55], v[12:13] op_sel_hi:[1,0,1]
	v_pk_fma_f32 v[14:15], v[42:43], v[54:55], v[14:15] op_sel_hi:[1,0,1]
	v_pk_fma_f32 v[8:9], v[40:41], v[58:59], v[8:9] op_sel_hi:[1,0,1]
	v_pk_fma_f32 v[10:11], v[42:43], v[58:59], v[10:11] op_sel_hi:[1,0,1]
	v_pk_fma_f32 v[0:1], v[40:41], v[66:67], v[0:1] op_sel_hi:[1,0,1]
	v_pk_fma_f32 v[2:3], v[42:43], v[66:67], v[2:3] op_sel_hi:[1,0,1]
	s_waitcnt vmcnt(4)
	v_pk_fma_f32 v[4:5], v[68:69], v[44:45], v[4:5] op_sel_hi:[0,1,1]
	v_pk_fma_f32 v[6:7], v[68:69], v[46:47], v[6:7] op_sel_hi:[0,1,1]
	v_pk_fma_f32 v[16:17], v[44:45], v[70:71], v[16:17] op_sel_hi:[1,0,1]
	v_pk_fma_f32 v[18:19], v[46:47], v[70:71], v[18:19] op_sel_hi:[1,0,1]
	v_pk_fma_f32 v[12:13], v[44:45], v[72:73], v[12:13] op_sel_hi:[1,0,1]
	v_pk_fma_f32 v[14:15], v[46:47], v[72:73], v[14:15] op_sel_hi:[1,0,1]
	v_pk_fma_f32 v[8:9], v[44:45], v[32:33], v[8:9] op_sel_hi:[1,0,1]
	v_pk_fma_f32 v[10:11], v[46:47], v[32:33], v[10:11] op_sel_hi:[1,0,1]
	v_pk_fma_f32 v[0:1], v[44:45], v[34:35], v[0:1] op_sel_hi:[1,0,1]
	v_pk_fma_f32 v[2:3], v[46:47], v[34:35], v[2:3] op_sel_hi:[1,0,1]
	ds_read_b128 v[48:51], v25 offset:8192
	ds_read_b128 v[52:55], v25 offset:16384
	ds_read_b128 v[56:59], v25 offset:24576
	ds_read_b128 v[60:63], v25
	ds_read_b128 v[64:67], v25 offset:32768
	s_waitcnt lgkmcnt(4)
	v_mov_b32_e32 v70, v51
	s_waitcnt lgkmcnt(3)
	v_mov_b32_e32 v72, v55
	s_waitcnt lgkmcnt(1)
	v_mov_b32_e32 v68, v63
	v_add_u32_e32 v25, 16, v25
	s_cmp_lg_u32 s6, 0x180000
	s_waitcnt vmcnt(3)
	v_pk_fma_f32 v[4:5], v[60:61], v[80:81], v[4:5] op_sel_hi:[0,1,1]
	v_pk_fma_f32 v[6:7], v[60:61], v[82:83], v[6:7] op_sel_hi:[0,1,1]
	v_pk_fma_f32 v[16:17], v[80:81], v[48:49], v[16:17] op_sel_hi:[1,0,1]
	v_pk_fma_f32 v[18:19], v[82:83], v[48:49], v[18:19] op_sel_hi:[1,0,1]
	v_pk_fma_f32 v[12:13], v[80:81], v[52:53], v[12:13] op_sel_hi:[1,0,1]
	v_pk_fma_f32 v[14:15], v[82:83], v[52:53], v[14:15] op_sel_hi:[1,0,1]
	v_pk_fma_f32 v[8:9], v[80:81], v[56:57], v[8:9] op_sel_hi:[1,0,1]
	v_pk_fma_f32 v[10:11], v[82:83], v[56:57], v[10:11] op_sel_hi:[1,0,1]
	s_waitcnt lgkmcnt(0)
	v_pk_fma_f32 v[0:1], v[80:81], v[64:65], v[0:1] op_sel_hi:[1,0,1]
	v_pk_fma_f32 v[2:3], v[82:83], v[64:65], v[2:3] op_sel_hi:[1,0,1]
	v_mov_b32_e32 v80, v59
	s_waitcnt vmcnt(2)
	v_pk_fma_f32 v[4:5], v[60:61], v[84:85], v[4:5] op_sel:[1,0,0]
	v_pk_fma_f32 v[6:7], v[60:61], v[86:87], v[6:7] op_sel:[1,0,0]
	v_pk_fma_f32 v[16:17], v[84:85], v[48:49], v[16:17] op_sel:[0,1,0]
	v_pk_fma_f32 v[18:19], v[86:87], v[48:49], v[18:19] op_sel:[0,1,0]
	v_pk_fma_f32 v[12:13], v[84:85], v[52:53], v[12:13] op_sel:[0,1,0]
	v_pk_fma_f32 v[14:15], v[86:87], v[52:53], v[14:15] op_sel:[0,1,0]
	v_pk_fma_f32 v[8:9], v[84:85], v[56:57], v[8:9] op_sel:[0,1,0]
	v_pk_fma_f32 v[10:11], v[86:87], v[56:57], v[10:11] op_sel:[0,1,0]
	v_pk_fma_f32 v[0:1], v[84:85], v[64:65], v[0:1] op_sel:[0,1,0]
	v_pk_fma_f32 v[2:3], v[86:87], v[64:65], v[2:3] op_sel:[0,1,0]
	v_mov_b32_e32 v82, v67
	s_waitcnt vmcnt(1)
	v_pk_fma_f32 v[4:5], v[62:63], v[88:89], v[4:5] op_sel_hi:[0,1,1]
	v_pk_fma_f32 v[6:7], v[62:63], v[90:91], v[6:7] op_sel_hi:[0,1,1]
	v_pk_fma_f32 v[16:17], v[88:89], v[50:51], v[16:17] op_sel_hi:[1,0,1]
	v_pk_fma_f32 v[18:19], v[90:91], v[50:51], v[18:19] op_sel_hi:[1,0,1]
	v_pk_fma_f32 v[12:13], v[88:89], v[54:55], v[12:13] op_sel_hi:[1,0,1]
	v_pk_fma_f32 v[14:15], v[90:91], v[54:55], v[14:15] op_sel_hi:[1,0,1]
	v_pk_fma_f32 v[8:9], v[88:89], v[58:59], v[8:9] op_sel_hi:[1,0,1]
	v_pk_fma_f32 v[10:11], v[90:91], v[58:59], v[10:11] op_sel_hi:[1,0,1]
	v_pk_fma_f32 v[0:1], v[88:89], v[66:67], v[0:1] op_sel_hi:[1,0,1]
	v_pk_fma_f32 v[2:3], v[90:91], v[66:67], v[2:3] op_sel_hi:[1,0,1]
	s_waitcnt vmcnt(0)
	v_pk_fma_f32 v[4:5], v[68:69], v[92:93], v[4:5] op_sel_hi:[0,1,1]
	v_pk_fma_f32 v[6:7], v[68:69], v[94:95], v[6:7] op_sel_hi:[0,1,1]
	v_pk_fma_f32 v[16:17], v[92:93], v[70:71], v[16:17] op_sel_hi:[1,0,1]
	v_pk_fma_f32 v[18:19], v[94:95], v[70:71], v[18:19] op_sel_hi:[1,0,1]
	v_pk_fma_f32 v[12:13], v[92:93], v[72:73], v[12:13] op_sel_hi:[1,0,1]
	v_pk_fma_f32 v[14:15], v[94:95], v[72:73], v[14:15] op_sel_hi:[1,0,1]
	v_pk_fma_f32 v[8:9], v[92:93], v[80:81], v[8:9] op_sel_hi:[1,0,1]
	v_pk_fma_f32 v[10:11], v[94:95], v[80:81], v[10:11] op_sel_hi:[1,0,1]
	v_pk_fma_f32 v[0:1], v[92:93], v[82:83], v[0:1] op_sel_hi:[1,0,1]
	v_pk_fma_f32 v[2:3], v[94:95], v[82:83], v[2:3] op_sel_hi:[1,0,1]
	s_cbranch_scc1 .LBB0_442
	ds_write_b128 v30, v[4:7] offset:40960
	ds_write_b128 v30, v[16:19] offset:41216
	ds_write_b128 v30, v[12:15] offset:41472
	ds_write_b128 v30, v[8:11] offset:41728
	ds_write_b128 v30, v[0:3] offset:41984
	s_waitcnt lgkmcnt(0)
	s_barrier
	s_and_saveexec_b64 s[6:7], vcc
	s_cbranch_execz .LBB0_440
	v_readlane_b32 s48, v251, 3
	v_readlane_b32 s49, v251, 4
	v_readlane_b32 s50, v251, 5
	v_readlane_b32 s51, v251, 6
	v_readlane_b32 s52, v251, 7
	v_readlane_b32 s53, v251, 8
	v_readlane_b32 s54, v251, 9
	v_readlane_b32 s55, v251, 10
	v_readlane_b32 s56, v251, 11
	v_readlane_b32 s57, v251, 12
	v_readlane_b32 s58, v251, 13
	v_readlane_b32 s59, v251, 14
	v_readlane_b32 s60, v251, 15
	v_readlane_b32 s61, v251, 16
	v_readlane_b32 s62, v251, 17
	v_readlane_b32 s63, v251, 18
	s_mov_b64 s[48:49], s[52:53]
	s_mul_i32 s3, s2, 0x6000
	s_mov_b64 s[50:51], s[54:55]
	s_mov_b64 s[52:53], s[56:57]
	s_mov_b64 s[54:55], s[58:59]
	s_mov_b64 s[56:57], s[60:61]
	s_mov_b64 s[58:59], s[62:63]
	s_mul_hi_i32 s1, s2, 0x6000
	s_add_u32 s3, s58, s3
	s_addc_u32 s1, s59, s1
	s_lshl_b64 s[4:5], s[4:5], 2
	s_add_u32 s8, s3, s4
	s_addc_u32 s9, s1, s5
	global_load_dword v31, v24, s[8:9]
	ds_read2st64_b32 v[0:1], v28 offset0:160 offset1:165
	ds_read2st64_b32 v[2:3], v28 offset0:170 offset1:175
	ds_read2st64_b32 v[4:5], v28 offset0:180 offset1:185
	ds_read2st64_b32 v[6:7], v28 offset0:190 offset1:195
	ds_read2st64_b32 v[8:9], v28 offset0:200 offset1:205
	ds_read2st64_b32 v[10:11], v28 offset0:210 offset1:215
	ds_read2st64_b32 v[12:13], v28 offset0:220 offset1:225
	ds_read2st64_b32 v[14:15], v28 offset0:230 offset1:235
	ds_read2st64_b32 v[16:17], v28 offset0:240 offset1:245
	ds_read2st64_b32 v[18:19], v28 offset0:250 offset1:255
	ds_read2st64_b32 v[26:27], v29 offset0:100 offset1:105
	ds_read2st64_b32 v[32:33], v29 offset0:110 offset1:115
	ds_read2st64_b32 v[34:35], v29 offset0:120 offset1:125
	ds_read2st64_b32 v[36:37], v29 offset0:130 offset1:135
	ds_read2st64_b32 v[38:39], v29 offset0:140 offset1:145
	ds_read2st64_b32 v[40:41], v29 offset0:150 offset1:155
	s_waitcnt lgkmcnt(14)
	v_add_f32_e32 v0, 0, v0
	v_add_f32_e32 v0, v0, v1
	v_add_f32_e32 v0, v0, v2
	v_add_f32_e32 v0, v0, v3
	s_waitcnt lgkmcnt(13)
	v_add_f32_e32 v0, v0, v4
	v_add_f32_e32 v0, v0, v5
	s_waitcnt lgkmcnt(12)
	v_add_f32_e32 v0, v0, v6
	v_add_f32_e32 v0, v0, v7
	s_waitcnt lgkmcnt(11)
	v_add_f32_e32 v0, v0, v8
	v_add_f32_e32 v0, v0, v9
	s_waitcnt lgkmcnt(10)
	v_add_f32_e32 v0, v0, v10
	v_add_f32_e32 v0, v0, v11
	s_waitcnt lgkmcnt(9)
	v_add_f32_e32 v0, v0, v12
	v_add_f32_e32 v0, v0, v13
	s_waitcnt lgkmcnt(8)
	v_add_f32_e32 v0, v0, v14
	v_add_f32_e32 v0, v0, v15
	s_waitcnt lgkmcnt(7)
	v_add_f32_e32 v0, v0, v16
	v_add_f32_e32 v0, v0, v17
	s_waitcnt lgkmcnt(6)
	v_add_f32_e32 v0, v0, v18
	v_add_f32_e32 v0, v0, v19
	s_waitcnt lgkmcnt(5)
	v_add_f32_e32 v0, v0, v26
	v_add_f32_e32 v0, v0, v27
	s_waitcnt lgkmcnt(4)
	v_add_f32_e32 v0, v0, v32
	v_add_f32_e32 v0, v0, v33
	s_waitcnt lgkmcnt(3)
	v_add_f32_e32 v0, v0, v34
	v_add_f32_e32 v0, v0, v35
	v_mad_u64_u32 v[42:43], s[2:3], s2, 5, v[22:23]
	s_waitcnt lgkmcnt(2)
	v_add_f32_e32 v0, v0, v36
	v_readlane_b32 s2, v251, 19
	v_add_f32_e32 v0, v0, v37
	v_readlane_b32 s3, v251, 20
	s_waitcnt lgkmcnt(1)
	v_add_f32_e32 v0, v0, v38
	v_add_f32_e32 v0, v0, v39
	v_mov_b64_e32 v[44:45], s[2:3]
	v_mad_i64_i32 v[42:43], s[2:3], v42, s97, v[44:45]
	s_waitcnt lgkmcnt(0)
	v_add_f32_e32 v0, v0, v40
	v_mov_b32_e32 v25, v129
	v_lshl_add_u64 v[42:43], v[42:43], 0, s[4:5]
	v_add_f32_e32 v0, v0, v41
	s_waitcnt vmcnt(0)
	v_add_f32_e32 v2, v0, v31
	v_lshl_add_u64 v[0:1], v[42:43], 0, v[24:25]
	global_store_dword v[0:1], v2, off
	s_branch .LBB0_440
